# P6 SwiGLU epilogue: fq-neighbour lanes exchange their two 64-column halves (v_permlane16_swap) so each lane stores 16 contiguous bytes: 8 dwordx4 stores per wave instead of 16 dwordx2
# baseline (speedup 1.0000x reference)
; __device__ __forceinline__ unsigned cvt_pk_bf16(float lo, float hi) { f32x2_t v = {lo, hi}; bf16x2_t b = __builtin_convertvector(v, bf16x2_t); return __builtin_bit_cast(unsigned, b); }
; __device__ __forceinline__ float sigmoidf_(float v) { return __builtin_amdgcn_rcpf(1.0f + __builtin_amdgcn_exp2f(-1.4426950408889634f * v)); }
; __device__ __forceinline__ f32x4 sig4(const f32x4 v) { return (f32x4){sigmoidf_(v[0]), sigmoidf_(v[1]), sigmoidf_(v[2]), sigmoidf_(v[3])}; }
;     __device__ __forceinline__ void operator()(const f32x4 (&acc)[2][2][4][2], const Unit& u, int wr, int wc, int fr, int fq) const {
;         const int row0 = u.pm * BM + wr * 64 + fr, col0 = u.pn * 128 + wc * 16 + 4 * fq;
; #pragma unroll
;         for (int ai = 0; ai < 2; ++ai)
; #pragma unroll
;             for (int m = 0; m < 4; ++m) { bf16_t* rowp = O + (size_t)(row0 + ai * HALF + m * 16) * 2816 + col0;
; #pragma unroll
;                 for (int bj = 0; bj < 2; ++bj) { const f32x4 g = acc[ai][bj][m][0], up = acc[ai][bj][m][1];
;                     const f32x4 o = g * sig4(g) * up; u32x2 w; w.x = cvt_pk_bf16(o[0], o[1]); w.y = cvt_pk_bf16(o[2], o[3]);
;                     *(u32x2*)(rowp + bj * 64) = w; } }
;     }
.LBB0_770:
	v_mul_f32_e32 v147, 0xbfb8aa3b, v124
	v_exp_f32_e32 v147, v147
	v_mul_f32_e32 v148, 0xbfb8aa3b, v125
	v_exp_f32_e32 v151, v148
	v_lshl_or_b32 v140, s41, 7, v144
	v_add_f32_e32 v147, 1.0, v147
	v_rcp_f32_e32 v150, v147
	v_add_f32_e32 v147, 1.0, v151
	v_mul_f32_e32 v151, 0xbfb8aa3b, v126
	v_exp_f32_e32 v152, v151
	v_mul_f32_e32 v151, 0xbfb8aa3b, v127
	v_exp_f32_e32 v153, v151
	v_rcp_f32_e32 v151, v147
	v_add_f32_e32 v147, 1.0, v152
	v_rcp_f32_e32 v152, v147
	v_add_f32_e32 v147, 1.0, v153
	v_pk_mul_f32 v[124:125], v[124:125], v[150:151]
	v_rcp_f32_e32 v153, v147
	v_pk_mul_f32 v[120:121], v[120:121], v[124:125]
	v_mul_f32_e32 v124, 0xbfb8aa3b, v116
	v_exp_f32_e32 v124, v124
	v_mul_f32_e32 v125, 0xbfb8aa3b, v117
	v_exp_f32_e32 v125, v125
	v_cvt_pk_bf16_f32 v120, v120, v121
	v_add_f32_e32 v121, 1.0, v124
	v_pk_mul_f32 v[126:127], v[126:127], v[152:153]
	v_rcp_f32_e32 v124, v121
	v_add_f32_e32 v121, 1.0, v125
	v_mul_f32_e32 v125, 0xbfb8aa3b, v118
	v_pk_mul_f32 v[122:123], v[122:123], v[126:127]
	v_exp_f32_e32 v126, v125
	v_mul_f32_e32 v125, 0xbfb8aa3b, v119
	v_exp_f32_e32 v127, v125
	v_rcp_f32_e32 v125, v121
	v_add_f32_e32 v121, 1.0, v126
	v_rcp_f32_e32 v126, v121
	v_add_f32_e32 v121, 1.0, v127
	v_rcp_f32_e32 v127, v121
	v_lshl_add_u32 v146, s52, 8, v142
	v_ashrrev_i32_e32 v141, 31, v140
	v_mov_b64_e32 v[138:139], s[16:17]
	v_pk_mul_f32 v[116:117], v[116:117], v[124:125]
	v_pk_mul_f32 v[118:119], v[118:119], v[126:127]
	v_mad_i64_i32 v[148:149], s[10:11], v146, s27, v[138:139]
	v_lshlrev_b64 v[140:141], 1, v[140:141]
	v_bfe_u32 v182, v218, 4, 1
	v_mul_u32_u24_e32 v182, 0x78, v182
	v_mov_b32_e32 v183, 0
	v_lshl_add_u64 v[140:141], v[182:183], 0, v[140:141]
	v_pk_mul_f32 v[114:115], v[114:115], v[118:119]
	v_pk_mul_f32 v[112:113], v[112:113], v[116:117]
	v_lshl_add_u64 v[148:149], v[148:149], 0, v[140:141]
	v_cvt_pk_bf16_f32 v112, v112, v113
	v_cvt_pk_bf16_f32 v113, v114, v115
	v_mov_b64_e32 v[156:157], v[112:113]
	v_mul_f32_e32 v112, 0xbfb8aa3b, v108
	v_mul_f32_e32 v113, 0xbfb8aa3b, v109
	v_exp_f32_e32 v112, v112
	v_exp_f32_e32 v113, v113
	v_mul_f32_e32 v114, 0xbfb8aa3b, v110
	v_mul_f32_e32 v115, 0xbfb8aa3b, v111
	v_add_f32_e32 v112, 1.0, v112
	v_add_f32_e32 v113, 1.0, v113
	v_rcp_f32_e32 v112, v112
	v_rcp_f32_e32 v113, v113
	v_exp_f32_e32 v114, v114
	v_exp_f32_e32 v115, v115
	v_or_b32_e32 v116, 16, v146
	v_pk_mul_f32 v[108:109], v[108:109], v[112:113]
	v_add_f32_e32 v114, 1.0, v114
	v_pk_mul_f32 v[104:105], v[104:105], v[108:109]
	v_mul_f32_e32 v108, 0xbfb8aa3b, v100
	v_add_f32_e32 v115, 1.0, v115
	v_exp_f32_e32 v108, v108
	v_mul_f32_e32 v109, 0xbfb8aa3b, v101
	v_rcp_f32_e32 v114, v114
	v_rcp_f32_e32 v115, v115
	v_exp_f32_e32 v109, v109
	v_cvt_pk_bf16_f32 v104, v104, v105
	v_add_f32_e32 v105, 1.0, v108
	v_pk_mul_f32 v[110:111], v[110:111], v[114:115]
	v_rcp_f32_e32 v108, v105
	v_add_f32_e32 v105, 1.0, v109
	v_mul_f32_e32 v109, 0xbfb8aa3b, v102
	v_pk_mul_f32 v[106:107], v[106:107], v[110:111]
	v_exp_f32_e32 v110, v109
	v_mul_f32_e32 v109, 0xbfb8aa3b, v103
	v_exp_f32_e32 v111, v109
	v_rcp_f32_e32 v109, v105
	v_add_f32_e32 v105, 1.0, v110
	v_rcp_f32_e32 v110, v105
	v_add_f32_e32 v105, 1.0, v111
	v_rcp_f32_e32 v111, v105
	v_pk_mul_f32 v[100:101], v[100:101], v[108:109]
	v_mad_i64_i32 v[116:117], s[10:11], v116, s27, v[138:139]
	v_pk_mul_f32 v[102:103], v[102:103], v[110:111]
	v_pk_mul_f32 v[96:97], v[96:97], v[100:101]
	v_pk_mul_f32 v[98:99], v[98:99], v[102:103]
	v_lshl_add_u64 v[116:117], v[116:117], 0, v[140:141]
	v_cvt_pk_bf16_f32 v96, v96, v97
	v_cvt_pk_bf16_f32 v97, v98, v99
	v_mov_b64_e32 v[160:161], v[96:97]
	v_mul_f32_e32 v96, 0xbfb8aa3b, v92
	v_mul_f32_e32 v97, 0xbfb8aa3b, v93
	v_exp_f32_e32 v96, v96
	v_exp_f32_e32 v97, v97
	v_mul_f32_e32 v98, 0xbfb8aa3b, v94
	v_mul_f32_e32 v99, 0xbfb8aa3b, v95
	v_add_f32_e32 v96, 1.0, v96
	v_add_f32_e32 v97, 1.0, v97
	v_rcp_f32_e32 v96, v96
	v_rcp_f32_e32 v97, v97
	v_exp_f32_e32 v98, v98
	v_exp_f32_e32 v99, v99
	v_or_b32_e32 v100, 32, v146
	v_pk_mul_f32 v[92:93], v[92:93], v[96:97]
	v_add_f32_e32 v98, 1.0, v98
	v_pk_mul_f32 v[88:89], v[88:89], v[92:93]
	v_mul_f32_e32 v92, 0xbfb8aa3b, v84
	v_add_f32_e32 v99, 1.0, v99
	v_exp_f32_e32 v92, v92
	v_mul_f32_e32 v93, 0xbfb8aa3b, v85
	v_rcp_f32_e32 v98, v98
	v_rcp_f32_e32 v99, v99
	v_exp_f32_e32 v93, v93
	v_cvt_pk_bf16_f32 v88, v88, v89
	v_add_f32_e32 v89, 1.0, v92
	v_pk_mul_f32 v[94:95], v[94:95], v[98:99]
	v_rcp_f32_e32 v92, v89
	v_add_f32_e32 v89, 1.0, v93
	v_mul_f32_e32 v93, 0xbfb8aa3b, v86
	v_pk_mul_f32 v[90:91], v[90:91], v[94:95]
	v_exp_f32_e32 v94, v93
	v_mul_f32_e32 v93, 0xbfb8aa3b, v87
	v_exp_f32_e32 v95, v93
	v_rcp_f32_e32 v93, v89
	v_add_f32_e32 v89, 1.0, v94
	v_rcp_f32_e32 v94, v89
	v_add_f32_e32 v89, 1.0, v95
	v_rcp_f32_e32 v95, v89
	v_pk_mul_f32 v[84:85], v[84:85], v[92:93]
	v_mad_i64_i32 v[100:101], s[10:11], v100, s27, v[138:139]
	v_pk_mul_f32 v[86:87], v[86:87], v[94:95]
	v_pk_mul_f32 v[80:81], v[80:81], v[84:85]
	v_pk_mul_f32 v[82:83], v[82:83], v[86:87]
	v_lshl_add_u64 v[100:101], v[100:101], 0, v[140:141]
	v_cvt_pk_bf16_f32 v80, v80, v81
	v_cvt_pk_bf16_f32 v81, v82, v83
	v_mov_b64_e32 v[164:165], v[80:81]
	v_mul_f32_e32 v80, 0xbfb8aa3b, v76
	v_mul_f32_e32 v81, 0xbfb8aa3b, v77
	v_exp_f32_e32 v80, v80
	v_exp_f32_e32 v81, v81
	v_mul_f32_e32 v82, 0xbfb8aa3b, v78
	v_mul_f32_e32 v83, 0xbfb8aa3b, v79
	v_add_f32_e32 v80, 1.0, v80
	v_add_f32_e32 v81, 1.0, v81
	v_rcp_f32_e32 v80, v80
	v_rcp_f32_e32 v81, v81
	v_exp_f32_e32 v82, v82
	v_exp_f32_e32 v83, v83
	v_or_b32_e32 v84, 48, v146
	v_pk_mul_f32 v[76:77], v[76:77], v[80:81]
	v_add_f32_e32 v82, 1.0, v82
	v_pk_mul_f32 v[72:73], v[72:73], v[76:77]
	v_mul_f32_e32 v76, 0xbfb8aa3b, v68
; __device__ __forceinline__ unsigned cvt_pk_bf16(float lo, float hi) { f32x2_t v = {lo, hi}; bf16x2_t b = __builtin_convertvector(v, bf16x2_t); return __builtin_bit_cast(unsigned, b); }
; __device__ __forceinline__ f32x4 sig4(const f32x4 v) { return (f32x4){sigmoidf_(v[0]), sigmoidf_(v[1]), sigmoidf_(v[2]), sigmoidf_(v[3])}; }
;     __device__ __forceinline__ void operator()(const f32x4 (&acc)[2][2][4][2], const Unit& u, int wr, int wc, int fr, int fq) const {
;         const int row0 = u.pm * BM + wr * 64 + fr, col0 = u.pn * 128 + wc * 16 + 4 * fq;
; #pragma unroll
;         for (int ai = 0; ai < 2; ++ai)
; #pragma unroll
;             for (int m = 0; m < 4; ++m) { bf16_t* rowp = O + (size_t)(row0 + ai * HALF + m * 16) * 2816 + col0;
; #pragma unroll
;                 for (int bj = 0; bj < 2; ++bj) { const f32x4 g = acc[ai][bj][m][0], up = acc[ai][bj][m][1];
;                     const f32x4 o = g * sig4(g) * up; u32x2 w; w.x = cvt_pk_bf16(o[0], o[1]); w.y = cvt_pk_bf16(o[2], o[3]);
;                     *(u32x2*)(rowp + bj * 64) = w; } }
;     }
	v_add_f32_e32 v83, 1.0, v83
	v_exp_f32_e32 v76, v76
	v_mul_f32_e32 v77, 0xbfb8aa3b, v69
	v_rcp_f32_e32 v82, v82
	v_rcp_f32_e32 v83, v83
	v_exp_f32_e32 v77, v77
	v_cvt_pk_bf16_f32 v72, v72, v73
	v_add_f32_e32 v73, 1.0, v76
	v_pk_mul_f32 v[78:79], v[78:79], v[82:83]
	v_rcp_f32_e32 v76, v73
	v_add_f32_e32 v73, 1.0, v77
	v_mul_f32_e32 v77, 0xbfb8aa3b, v70
	v_pk_mul_f32 v[74:75], v[74:75], v[78:79]
	v_exp_f32_e32 v78, v77
	v_mul_f32_e32 v77, 0xbfb8aa3b, v71
	v_exp_f32_e32 v79, v77
	v_rcp_f32_e32 v77, v73
	v_add_f32_e32 v73, 1.0, v78
	v_rcp_f32_e32 v78, v73
	v_add_f32_e32 v73, 1.0, v79
	v_rcp_f32_e32 v79, v73
	v_pk_mul_f32 v[68:69], v[68:69], v[76:77]
	v_mad_i64_i32 v[84:85], s[10:11], v84, s27, v[138:139]
	v_pk_mul_f32 v[70:71], v[70:71], v[78:79]
	v_pk_mul_f32 v[64:65], v[64:65], v[68:69]
	v_pk_mul_f32 v[66:67], v[66:67], v[70:71]
	v_lshl_add_u64 v[84:85], v[84:85], 0, v[140:141]
	v_cvt_pk_bf16_f32 v64, v64, v65
	v_cvt_pk_bf16_f32 v65, v66, v67
	v_mov_b64_e32 v[168:169], v[64:65]
	v_mul_f32_e32 v64, 0xbfb8aa3b, v60
	v_mul_f32_e32 v65, 0xbfb8aa3b, v61
	v_exp_f32_e32 v64, v64
	v_exp_f32_e32 v65, v65
	v_mul_f32_e32 v66, 0xbfb8aa3b, v62
	v_mul_f32_e32 v67, 0xbfb8aa3b, v63
	v_add_f32_e32 v64, 1.0, v64
	v_add_f32_e32 v65, 1.0, v65
	v_rcp_f32_e32 v64, v64
	v_rcp_f32_e32 v65, v65
	v_exp_f32_e32 v66, v66
	v_exp_f32_e32 v67, v67
	v_add_u32_e32 v68, 0x80, v146
	v_pk_mul_f32 v[60:61], v[60:61], v[64:65]
	v_add_f32_e32 v66, 1.0, v66
	v_pk_mul_f32 v[56:57], v[56:57], v[60:61]
	v_mul_f32_e32 v60, 0xbfb8aa3b, v52
	v_add_f32_e32 v67, 1.0, v67
	v_exp_f32_e32 v60, v60
	v_mul_f32_e32 v61, 0xbfb8aa3b, v53
	v_rcp_f32_e32 v66, v66
	v_rcp_f32_e32 v67, v67
	v_exp_f32_e32 v61, v61
	v_cvt_pk_bf16_f32 v56, v56, v57
	v_add_f32_e32 v57, 1.0, v60
	v_pk_mul_f32 v[62:63], v[62:63], v[66:67]
	v_rcp_f32_e32 v60, v57
	v_add_f32_e32 v57, 1.0, v61
	v_mul_f32_e32 v61, 0xbfb8aa3b, v54
	v_pk_mul_f32 v[58:59], v[58:59], v[62:63]
	v_exp_f32_e32 v62, v61
	v_mul_f32_e32 v61, 0xbfb8aa3b, v55
	v_exp_f32_e32 v63, v61
	v_rcp_f32_e32 v61, v57
	v_add_f32_e32 v57, 1.0, v62
	v_rcp_f32_e32 v62, v57
	v_add_f32_e32 v57, 1.0, v63
	v_rcp_f32_e32 v63, v57
	v_pk_mul_f32 v[52:53], v[52:53], v[60:61]
	v_mad_i64_i32 v[68:69], s[10:11], v68, s27, v[138:139]
	v_pk_mul_f32 v[54:55], v[54:55], v[62:63]
	v_pk_mul_f32 v[48:49], v[48:49], v[52:53]
	v_pk_mul_f32 v[50:51], v[50:51], v[54:55]
	v_lshl_add_u64 v[68:69], v[68:69], 0, v[140:141]
	v_cvt_pk_bf16_f32 v48, v48, v49
	v_cvt_pk_bf16_f32 v49, v50, v51
	v_mov_b64_e32 v[172:173], v[48:49]
	v_mul_f32_e32 v48, 0xbfb8aa3b, v44
	v_mul_f32_e32 v49, 0xbfb8aa3b, v45
	v_exp_f32_e32 v48, v48
	v_exp_f32_e32 v49, v49
	v_mul_f32_e32 v50, 0xbfb8aa3b, v46
	v_mul_f32_e32 v51, 0xbfb8aa3b, v47
	v_add_f32_e32 v48, 1.0, v48
	v_add_f32_e32 v49, 1.0, v49
	v_rcp_f32_e32 v48, v48
	v_rcp_f32_e32 v49, v49
	v_exp_f32_e32 v50, v50
	v_exp_f32_e32 v51, v51
	v_add_u32_e32 v52, 0x90, v146
	v_pk_mul_f32 v[44:45], v[44:45], v[48:49]
	v_add_f32_e32 v50, 1.0, v50
	v_pk_mul_f32 v[40:41], v[40:41], v[44:45]
	v_mul_f32_e32 v44, 0xbfb8aa3b, v36
	v_add_f32_e32 v51, 1.0, v51
	v_exp_f32_e32 v44, v44
	v_mul_f32_e32 v45, 0xbfb8aa3b, v37
	v_rcp_f32_e32 v50, v50
	v_rcp_f32_e32 v51, v51
	v_exp_f32_e32 v45, v45
	v_cvt_pk_bf16_f32 v40, v40, v41
	v_add_f32_e32 v41, 1.0, v44
	v_pk_mul_f32 v[46:47], v[46:47], v[50:51]
	v_rcp_f32_e32 v44, v41
	v_add_f32_e32 v41, 1.0, v45
	v_mul_f32_e32 v45, 0xbfb8aa3b, v38
	v_pk_mul_f32 v[42:43], v[42:43], v[46:47]
	v_exp_f32_e32 v46, v45
	v_mul_f32_e32 v45, 0xbfb8aa3b, v39
	v_exp_f32_e32 v47, v45
	v_rcp_f32_e32 v45, v41
	v_add_f32_e32 v41, 1.0, v46
	v_rcp_f32_e32 v46, v41
	v_add_f32_e32 v41, 1.0, v47
	v_rcp_f32_e32 v47, v41
	v_pk_mul_f32 v[36:37], v[36:37], v[44:45]
	v_mad_i64_i32 v[52:53], s[10:11], v52, s27, v[138:139]
	v_pk_mul_f32 v[38:39], v[38:39], v[46:47]
	v_pk_mul_f32 v[32:33], v[32:33], v[36:37]
	v_pk_mul_f32 v[34:35], v[34:35], v[38:39]
	v_lshl_add_u64 v[52:53], v[52:53], 0, v[140:141]
	v_cvt_pk_bf16_f32 v32, v32, v33
	v_cvt_pk_bf16_f32 v33, v34, v35
	v_mov_b64_e32 v[176:177], v[32:33]
	v_mul_f32_e32 v32, 0xbfb8aa3b, v28
	v_mul_f32_e32 v33, 0xbfb8aa3b, v29
	v_exp_f32_e32 v32, v32
	v_exp_f32_e32 v33, v33
	v_mul_f32_e32 v34, 0xbfb8aa3b, v30
	v_mul_f32_e32 v35, 0xbfb8aa3b, v31
	v_add_f32_e32 v32, 1.0, v32
	v_add_f32_e32 v33, 1.0, v33
	v_rcp_f32_e32 v32, v32
	v_rcp_f32_e32 v33, v33
	v_exp_f32_e32 v34, v34
	v_exp_f32_e32 v35, v35
; __device__ __forceinline__ unsigned cvt_pk_bf16(float lo, float hi) { f32x2_t v = {lo, hi}; bf16x2_t b = __builtin_convertvector(v, bf16x2_t); return __builtin_bit_cast(unsigned, b); }
; __device__ __forceinline__ f32x4 sig4(const f32x4 v) { return (f32x4){sigmoidf_(v[0]), sigmoidf_(v[1]), sigmoidf_(v[2]), sigmoidf_(v[3])}; }
;     __device__ __forceinline__ void operator()(const f32x4 (&acc)[2][2][4][2], const Unit& u, int wr, int wc, int fr, int fq) const {
;         const int row0 = u.pm * BM + wr * 64 + fr, col0 = u.pn * 128 + wc * 16 + 4 * fq;
; #pragma unroll
;         for (int ai = 0; ai < 2; ++ai)
; #pragma unroll
;             for (int m = 0; m < 4; ++m) { bf16_t* rowp = O + (size_t)(row0 + ai * HALF + m * 16) * 2816 + col0;
; #pragma unroll
;                 for (int bj = 0; bj < 2; ++bj) { const f32x4 g = acc[ai][bj][m][0], up = acc[ai][bj][m][1];
;                     const f32x4 o = g * sig4(g) * up; u32x2 w; w.x = cvt_pk_bf16(o[0], o[1]); w.y = cvt_pk_bf16(o[2], o[3]);
;                     *(u32x2*)(rowp + bj * 64) = w; } }
;     }
	v_add_u32_e32 v36, 0xa0, v146
	v_pk_mul_f32 v[28:29], v[28:29], v[32:33]
	v_add_f32_e32 v34, 1.0, v34
	v_pk_mul_f32 v[24:25], v[24:25], v[28:29]
	v_mul_f32_e32 v28, 0xbfb8aa3b, v20
	v_add_f32_e32 v35, 1.0, v35
	v_exp_f32_e32 v28, v28
	v_mul_f32_e32 v29, 0xbfb8aa3b, v21
	v_rcp_f32_e32 v34, v34
	v_rcp_f32_e32 v35, v35
	v_exp_f32_e32 v29, v29
	v_cvt_pk_bf16_f32 v24, v24, v25
	v_add_f32_e32 v25, 1.0, v28
	v_pk_mul_f32 v[30:31], v[30:31], v[34:35]
	v_rcp_f32_e32 v28, v25
	v_add_f32_e32 v25, 1.0, v29
	v_mul_f32_e32 v29, 0xbfb8aa3b, v22
	v_pk_mul_f32 v[26:27], v[26:27], v[30:31]
	v_exp_f32_e32 v30, v29
	v_mul_f32_e32 v29, 0xbfb8aa3b, v23
	v_exp_f32_e32 v31, v29
	v_rcp_f32_e32 v29, v25
	v_add_f32_e32 v25, 1.0, v30
	v_rcp_f32_e32 v30, v25
	v_add_f32_e32 v25, 1.0, v31
	v_rcp_f32_e32 v31, v25
	v_pk_mul_f32 v[20:21], v[20:21], v[28:29]
	v_mad_i64_i32 v[36:37], s[10:11], v36, s27, v[138:139]
	v_pk_mul_f32 v[22:23], v[22:23], v[30:31]
	v_pk_mul_f32 v[16:17], v[16:17], v[20:21]
	v_pk_mul_f32 v[18:19], v[18:19], v[22:23]
	v_lshl_add_u64 v[36:37], v[36:37], 0, v[140:141]
	v_cvt_pk_bf16_f32 v16, v16, v17
	v_cvt_pk_bf16_f32 v17, v18, v19
	v_mov_b64_e32 v[180:181], v[16:17]
	v_mul_f32_e32 v16, 0xbfb8aa3b, v12
	v_mul_f32_e32 v17, 0xbfb8aa3b, v13
	v_exp_f32_e32 v16, v16
	v_exp_f32_e32 v17, v17
	v_mul_f32_e32 v18, 0xbfb8aa3b, v14
	v_mul_f32_e32 v19, 0xbfb8aa3b, v15
	v_add_f32_e32 v16, 1.0, v16
	v_add_f32_e32 v17, 1.0, v17
	v_rcp_f32_e32 v16, v16
	v_rcp_f32_e32 v17, v17
	v_exp_f32_e32 v18, v18
	v_exp_f32_e32 v19, v19
	v_add_u32_e32 v20, 0xb0, v146
	v_pk_mul_f32 v[12:13], v[12:13], v[16:17]
	v_add_f32_e32 v18, 1.0, v18
	v_pk_mul_f32 v[8:9], v[8:9], v[12:13]
	v_mul_f32_e32 v12, 0xbfb8aa3b, v4
	v_add_f32_e32 v19, 1.0, v19
	v_exp_f32_e32 v12, v12
	v_mul_f32_e32 v13, 0xbfb8aa3b, v5
	v_rcp_f32_e32 v18, v18
	v_rcp_f32_e32 v19, v19
	v_exp_f32_e32 v13, v13
	v_cvt_pk_bf16_f32 v8, v8, v9
	v_add_f32_e32 v9, 1.0, v12
	v_pk_mul_f32 v[14:15], v[14:15], v[18:19]
	v_rcp_f32_e32 v12, v9
	v_add_f32_e32 v9, 1.0, v13
	v_mul_f32_e32 v13, 0xbfb8aa3b, v6
	v_pk_mul_f32 v[10:11], v[10:11], v[14:15]
	v_exp_f32_e32 v14, v13
	v_mul_f32_e32 v13, 0xbfb8aa3b, v7
	v_exp_f32_e32 v15, v13
	v_rcp_f32_e32 v13, v9
	v_add_f32_e32 v9, 1.0, v14
	v_rcp_f32_e32 v14, v9
	v_add_f32_e32 v9, 1.0, v15
	v_rcp_f32_e32 v15, v9
	v_pk_mul_f32 v[4:5], v[4:5], v[12:13]
	v_mad_i64_i32 v[20:21], s[10:11], v20, s27, v[138:139]
	v_pk_mul_f32 v[6:7], v[6:7], v[14:15]
	v_pk_mul_f32 v[0:1], v[0:1], v[4:5]
	v_pk_mul_f32 v[2:3], v[2:3], v[6:7]
	v_cvt_pk_bf16_f32 v121, v122, v123
	v_cvt_pk_bf16_f32 v105, v106, v107
	v_cvt_pk_bf16_f32 v89, v90, v91
	v_cvt_pk_bf16_f32 v73, v74, v75
	v_cvt_pk_bf16_f32 v57, v58, v59
	v_cvt_pk_bf16_f32 v41, v42, v43
	v_cvt_pk_bf16_f32 v25, v26, v27
	v_lshl_add_u64 v[20:21], v[20:21], 0, v[140:141]
	v_cvt_pk_bf16_f32 v9, v10, v11
	v_cvt_pk_bf16_f32 v0, v0, v1
	v_cvt_pk_bf16_f32 v1, v2, v3
	s_andn2_b64 vcc, exec, s[42:43]
	s_mov_b64 s[42:43], -1
	v_mov_b64_e32 v[154:155], v[120:121]
	v_mov_b64_e32 v[158:159], v[104:105]
	v_mov_b64_e32 v[162:163], v[88:89]
	v_mov_b64_e32 v[166:167], v[72:73]
	v_mov_b64_e32 v[170:171], v[56:57]
	v_mov_b64_e32 v[174:175], v[40:41]
	v_mov_b64_e32 v[178:179], v[24:25]
	v_mov_b64_e32 v[198:199], v[8:9]
	v_mov_b64_e32 v[200:201], v[0:1]
	s_nop 1
	v_permlane16_swap_b32_e32 v154, v156
	v_permlane16_swap_b32_e32 v155, v157
	global_store_dwordx4 v[148:149], v[154:157], off
	v_permlane16_swap_b32_e32 v158, v160
	v_permlane16_swap_b32_e32 v159, v161
	global_store_dwordx4 v[116:117], v[158:161], off
	v_permlane16_swap_b32_e32 v162, v164
	v_permlane16_swap_b32_e32 v163, v165
	global_store_dwordx4 v[100:101], v[162:165], off
	v_permlane16_swap_b32_e32 v166, v168
	v_permlane16_swap_b32_e32 v167, v169
	global_store_dwordx4 v[84:85], v[166:169], off
	v_permlane16_swap_b32_e32 v170, v172
	v_permlane16_swap_b32_e32 v171, v173
	global_store_dwordx4 v[68:69], v[170:173], off
	v_permlane16_swap_b32_e32 v174, v176
	v_permlane16_swap_b32_e32 v175, v177
	global_store_dwordx4 v[52:53], v[174:177], off
	v_permlane16_swap_b32_e32 v178, v180
	v_permlane16_swap_b32_e32 v179, v181
	global_store_dwordx4 v[36:37], v[178:181], off
	v_permlane16_swap_b32_e32 v198, v200
	v_permlane16_swap_b32_e32 v199, v201
	global_store_dwordx4 v[20:21], v[198:201], off
	s_cbranch_vccnz .LBB0_763
	s_andn2_b64 vcc, exec, s[22:23]
	s_cbranch_vccnz .LBB0_762
	s_barrier
	s_branch .LBB0_762
